# epilogue de-serialisation: P1 SWIGLU ssq row-scale loads hoisted above the ALIGN_EPI barrier (on top of nt P0 loads + XCD-local seams)
# speedup vs baseline: 1.0891x; 1.0054x over previous
; #define PG8_STAGE(bufoff, gbase, voff) do { _Pragma("unroll") for (int _i = 0; _i < 2; ++_i) \
;         __builtin_amdgcn_global_load_lds((const unsigned*)((const char*)(gbase) + (voff)[_i]), (LAS unsigned*)(lds + (bufoff) + ldsw + _i * 8192), 16, 0, 0); } while (0)
; #define PG8_LDA(dst, b, h) do { _Pragma("unroll") for (int m = 0; m < 4; ++m) _Pragma("unroll") for (int k = 0; k < 2; ++k) dst[m][k] = *(const LAS bf16x8*)(lds + PG8_SA(b, h) + aoff + m * 2048 + k * 1024); } while (0)
; #define PG8_LDB(dst, b, h) do { _Pragma("unroll") for (int n = 0; n < 2; ++n) _Pragma("unroll") for (int k = 0; k < 2; ++k) dst[n][k] = *(const LAS bf16x8*)(lds + PG8_SB(b, h) + boff + n * 2048 + k * 1024); } while (0)
; #define PG8_MMA(ai, bj, At, Bt) do { __builtin_amdgcn_s_setprio(1); _Pragma("unroll") for (int m = 0; m < 4; ++m) _Pragma("unroll") for (int n = 0; n < 2; ++n) _Pragma("unroll") for (int k = 0; k < 2; ++k) \
;         acc[ai][bj][m][n] = __builtin_amdgcn_mfma_f32_16x16x32_bf16(Bt[n][k], At[m][k], acc[ai][bj][m][n], 0, 0, 0); __builtin_amdgcn_s_setprio(0); } while (0)
; #define PG8_WAIT_V(n) asm volatile("s_waitcnt vmcnt(" #n ")" ::: "memory")
; #define PG8_WAIT_L(n) asm volatile("s_waitcnt lgkmcnt(" #n ")" ::: "memory")
; #define PG8_BAR __builtin_amdgcn_s_barrier()
; #define PG8_SCHED __builtin_amdgcn_sched_barrier(0)
; __device__ __forceinline__ void gemm_phase(LAS unsigned char* lds, const Gemm g, const StaticOrder S, const Epi E) {
;     ...
;             PG8_LDB(B0, 0, 0); PG8_LDB(B1, 0, 1); PG8_SCHED; PG8_LDA(At, 0, 0); PG8_STAGE(PG8_SA(1, 1), a1 + hstepA, voffA);
;             PG8_WAIT_V(8); PG8_WAIT_L(0); PG8_BAR; PG8_MMA(0, 0, At, B0); PG8_MMA(0, 1, At, B1); PG8_BAR; PG8_SCHED;
;             if (full) PG8_LDA(At, 0, 1); PG8_STAGE(PG8_SB(0, 0), b2, voffB); PG8_STAGE(PG8_SB(0, 1), b2 + hstepB, voffB); PG8_STAGE(PG8_SA(0, 0), a2, voffA);
;             PG8_WAIT_V(8); PG8_WAIT_L(0); PG8_BAR; if (full) { PG8_MMA(1, 0, At, B0); PG8_MMA(1, 1, At, B1); } PG8_BAR; PG8_SCHED;
.LBB0_305:
	ds_read_b128 v[142:145], v137
	ds_read_b128 v[154:157], v137 offset:1024
	ds_read_b128 v[158:161], v137 offset:2048
	ds_read_b128 v[166:169], v137 offset:3072
	ds_read_b128 v[170:173], v138
	ds_read_b128 v[174:177], v138 offset:1024
	ds_read_b128 v[178:181], v138 offset:2048
	ds_read_b128 v[182:185], v138 offset:3072
	s_add_u32 s42, s40, 0xfffc0080
	s_addc_u32 s43, s41, -1
	s_cmp_eq_u32 s63, 12
	s_cselect_b32 s45, s27, s43
	s_cselect_b32 s44, s26, s42
	s_cselect_b32 s43, s37, s25
	s_cselect_b32 s42, s36, s23
	v_lshl_add_u64 v[134:135], s[40:41], 0, v[146:147]
	s_add_i32 m0, s39, 0xc000
	ds_read_b128 v[186:189], v139
	ds_read_b128 v[190:193], v139 offset:1024
	ds_read_b128 v[194:197], v139 offset:2048
	ds_read_b128 v[200:203], v139 offset:3072
	ds_read_b128 v[204:207], v139 offset:4096
	ds_read_b128 v[208:211], v139 offset:5120
	ds_read_b128 v[212:215], v139 offset:6144
	ds_read_b128 v[216:219], v139 offset:7168
	global_load_lds_dwordx4 v[134:135], off
	v_lshl_add_u64 v[134:135], s[40:41], 0, v[150:151]
	s_add_i32 m0, s39, 0xe000
	s_nop 0
	global_load_lds_dwordx4 v[134:135], off
	s_waitcnt vmcnt(8)
	s_waitcnt lgkmcnt(0)
	s_barrier
	s_setprio 1
	s_waitcnt lgkmcnt(0)
	v_mfma_f32_16x16x32_bf16 v[118:121], v[142:145], v[186:189], v[118:121]
	v_mfma_f32_16x16x32_bf16 v[114:117], v[158:161], v[186:189], v[114:117]
	v_mfma_f32_16x16x32_bf16 v[106:109], v[142:145], v[194:197], v[106:109]
	v_mfma_f32_16x16x32_bf16 v[102:105], v[158:161], v[194:197], v[102:105]
	v_mfma_f32_16x16x32_bf16 v[94:97], v[142:145], v[204:207], v[94:97]
	v_mfma_f32_16x16x32_bf16 v[86:89], v[158:161], v[204:207], v[86:89]
	v_mfma_f32_16x16x32_bf16 v[78:81], v[142:145], v[212:215], v[78:81]
	v_mfma_f32_16x16x32_bf16 v[70:73], v[158:161], v[212:215], v[70:73]
	v_mfma_f32_16x16x32_bf16 v[118:121], v[154:157], v[190:193], v[118:121]
	v_mfma_f32_16x16x32_bf16 v[114:117], v[166:169], v[190:193], v[114:117]
	v_mfma_f32_16x16x32_bf16 v[106:109], v[154:157], v[200:203], v[106:109]
	v_mfma_f32_16x16x32_bf16 v[102:105], v[166:169], v[200:203], v[102:105]
	v_mfma_f32_16x16x32_bf16 v[94:97], v[154:157], v[208:211], v[94:97]
	v_mfma_f32_16x16x32_bf16 v[86:89], v[166:169], v[208:211], v[86:89]
	v_mfma_f32_16x16x32_bf16 v[78:81], v[154:157], v[216:219], v[78:81]
	v_mfma_f32_16x16x32_bf16 v[70:73], v[166:169], v[216:219], v[70:73]
	s_setprio 0
	s_setprio 1
	v_mfma_f32_16x16x32_bf16 v[126:129], v[170:173], v[186:189], v[126:129]
	v_mfma_f32_16x16x32_bf16 v[122:125], v[178:181], v[186:189], v[122:125]
	v_mfma_f32_16x16x32_bf16 v[110:113], v[170:173], v[194:197], v[110:113]
	v_mfma_f32_16x16x32_bf16 v[98:101], v[178:181], v[194:197], v[98:101]
	v_mfma_f32_16x16x32_bf16 v[90:93], v[170:173], v[204:207], v[90:93]
	v_mfma_f32_16x16x32_bf16 v[82:85], v[178:181], v[204:207], v[82:85]
	v_mfma_f32_16x16x32_bf16 v[74:77], v[170:173], v[212:215], v[74:77]
	v_mfma_f32_16x16x32_bf16 v[66:69], v[178:181], v[212:215], v[66:69]
	v_mfma_f32_16x16x32_bf16 v[126:129], v[174:177], v[190:193], v[126:129]
	v_mfma_f32_16x16x32_bf16 v[122:125], v[182:185], v[190:193], v[122:125]
	v_mfma_f32_16x16x32_bf16 v[110:113], v[174:177], v[200:203], v[110:113]
	v_mfma_f32_16x16x32_bf16 v[98:101], v[182:185], v[200:203], v[98:101]
	v_mfma_f32_16x16x32_bf16 v[90:93], v[174:177], v[208:211], v[90:93]
	v_mfma_f32_16x16x32_bf16 v[82:85], v[182:185], v[208:211], v[82:85]
	v_mfma_f32_16x16x32_bf16 v[74:77], v[174:177], v[216:219], v[74:77]
	v_mfma_f32_16x16x32_bf16 v[66:69], v[182:185], v[216:219], v[66:69]
	s_setprio 0
	s_barrier
	s_add_i32 s64, s58, s46
	v_lshl_add_u64 v[134:135], s[42:43], 0, v[148:149]
	s_mov_b32 m0, s64
	ds_read_b128 v[186:189], v139 offset:16384
	ds_read_b128 v[190:193], v139 offset:17408
	ds_read_b128 v[194:197], v139 offset:18432
	ds_read_b128 v[200:203], v139 offset:19456
	ds_read_b128 v[204:207], v139 offset:20480
	ds_read_b128 v[208:211], v139 offset:21504
	ds_read_b128 v[212:215], v139 offset:22528
	ds_read_b128 v[216:219], v139 offset:23552
	global_load_lds_dwordx4 v[134:135], off
	s_add_i32 m0, s64, 0x2000
	s_add_u32 s64, s42, 0x40000
	v_lshl_add_u64 v[220:221], s[42:43], 0, v[152:153]
	s_addc_u32 s65, s43, 0
	s_add_i32 s69, s59, s46
	global_load_lds_dwordx4 v[220:221], off
	v_lshl_add_u64 v[222:223], s[64:65], 0, v[148:149]
	s_mov_b32 m0, s69
	v_lshl_add_u64 v[224:225], s[44:45], 0, v[150:151]
	global_load_lds_dwordx4 v[222:223], off
	v_lshl_add_u64 v[222:223], s[64:65], 0, v[152:153]
	s_add_i32 m0, s69, 0x2000
	s_nop 0
	global_load_lds_dwordx4 v[222:223], off
	v_lshl_add_u64 v[222:223], s[44:45], 0, v[146:147]
	s_mov_b32 m0, s39
	s_nop 0
	global_load_lds_dwordx4 v[222:223], off
	s_mov_b32 m0, s49
	s_nop 0
	global_load_lds_dwordx4 v[224:225], off
	s_waitcnt vmcnt(8)
	s_waitcnt lgkmcnt(0)
	s_barrier
; #define PG8_STAGE(bufoff, gbase, voff) do { _Pragma("unroll") for (int _i = 0; _i < 2; ++_i) \
;         __builtin_amdgcn_global_load_lds((const unsigned*)((const char*)(gbase) + (voff)[_i]), (LAS unsigned*)(lds + (bufoff) + ldsw + _i * 8192), 16, 0, 0); } while (0)
; #define PG8_LDA(dst, b, h) do { _Pragma("unroll") for (int m = 0; m < 4; ++m) _Pragma("unroll") for (int k = 0; k < 2; ++k) dst[m][k] = *(const LAS bf16x8*)(lds + PG8_SA(b, h) + aoff + m * 2048 + k * 1024); } while (0)
; #define PG8_LDB(dst, b, h) do { _Pragma("unroll") for (int n = 0; n < 2; ++n) _Pragma("unroll") for (int k = 0; k < 2; ++k) dst[n][k] = *(const LAS bf16x8*)(lds + PG8_SB(b, h) + boff + n * 2048 + k * 1024); } while (0)
; #define PG8_MMA(ai, bj, At, Bt) do { __builtin_amdgcn_s_setprio(1); _Pragma("unroll") for (int m = 0; m < 4; ++m) _Pragma("unroll") for (int n = 0; n < 2; ++n) _Pragma("unroll") for (int k = 0; k < 2; ++k) \
;         acc[ai][bj][m][n] = __builtin_amdgcn_mfma_f32_16x16x32_bf16(Bt[n][k], At[m][k], acc[ai][bj][m][n], 0, 0, 0); __builtin_amdgcn_s_setprio(0); } while (0)
; #define PG8_WAIT_V(n) asm volatile("s_waitcnt vmcnt(" #n ")" ::: "memory")
; #define PG8_WAIT_L(n) asm volatile("s_waitcnt lgkmcnt(" #n ")" ::: "memory")
; #define PG8_BAR __builtin_amdgcn_s_barrier()
; #define PG8_SCHED __builtin_amdgcn_sched_barrier(0)
; __device__ __forceinline__ void gemm_phase(LAS unsigned char* lds, const Gemm g, const StaticOrder S, const Epi E) {
;     ...
;             PG8_WAIT_V(8); PG8_WAIT_L(0); PG8_BAR; if (full) { PG8_MMA(1, 0, At, B0); PG8_MMA(1, 1, At, B1); } PG8_BAR; PG8_SCHED;
;             PG8_LDB(B0, 1, 0); PG8_LDB(B1, 1, 1); PG8_SCHED; PG8_LDA(At, 1, 0); PG8_STAGE(PG8_SA(0, 1), a2 + hstepA, voffA);
;             PG8_WAIT_V(8); PG8_WAIT_L(0); PG8_BAR; PG8_MMA(0, 0, At, B0); PG8_MMA(0, 1, At, B1); PG8_BAR; PG8_SCHED;
	s_setprio 1
	s_waitcnt lgkmcnt(0)
	v_mfma_f32_16x16x32_bf16 v[62:65], v[142:145], v[186:189], v[62:65]
	v_mfma_f32_16x16x32_bf16 v[54:57], v[158:161], v[186:189], v[54:57]
	v_mfma_f32_16x16x32_bf16 v[46:49], v[142:145], v[194:197], v[46:49]
	v_mfma_f32_16x16x32_bf16 v[38:41], v[158:161], v[194:197], v[38:41]
	v_mfma_f32_16x16x32_bf16 v[30:33], v[142:145], v[204:207], v[30:33]
	v_mfma_f32_16x16x32_bf16 v[22:25], v[158:161], v[204:207], v[22:25]
	v_mfma_f32_16x16x32_bf16 v[14:17], v[142:145], v[212:215], v[14:17]
	v_mfma_f32_16x16x32_bf16 v[6:9], v[158:161], v[212:215], v[6:9]
	v_mfma_f32_16x16x32_bf16 v[62:65], v[154:157], v[190:193], v[62:65]
	v_mfma_f32_16x16x32_bf16 v[54:57], v[166:169], v[190:193], v[54:57]
	v_mfma_f32_16x16x32_bf16 v[46:49], v[154:157], v[200:203], v[46:49]
	v_mfma_f32_16x16x32_bf16 v[38:41], v[166:169], v[200:203], v[38:41]
	v_mfma_f32_16x16x32_bf16 v[30:33], v[154:157], v[208:211], v[30:33]
	v_mfma_f32_16x16x32_bf16 v[22:25], v[166:169], v[208:211], v[22:25]
	v_mfma_f32_16x16x32_bf16 v[14:17], v[154:157], v[216:219], v[14:17]
	v_mfma_f32_16x16x32_bf16 v[6:9], v[166:169], v[216:219], v[6:9]
	s_setprio 0
	s_setprio 1
	v_mfma_f32_16x16x32_bf16 v[58:61], v[170:173], v[186:189], v[58:61]
	v_mfma_f32_16x16x32_bf16 v[50:53], v[178:181], v[186:189], v[50:53]
	v_mfma_f32_16x16x32_bf16 v[42:45], v[170:173], v[194:197], v[42:45]
	v_mfma_f32_16x16x32_bf16 v[34:37], v[178:181], v[194:197], v[34:37]
	v_mfma_f32_16x16x32_bf16 v[26:29], v[170:173], v[204:207], v[26:29]
	v_mfma_f32_16x16x32_bf16 v[18:21], v[178:181], v[204:207], v[18:21]
	v_mfma_f32_16x16x32_bf16 v[10:13], v[170:173], v[212:215], v[10:13]
	v_mfma_f32_16x16x32_bf16 v[2:5], v[178:181], v[212:215], v[2:5]
	v_mfma_f32_16x16x32_bf16 v[58:61], v[174:177], v[190:193], v[58:61]
	v_mfma_f32_16x16x32_bf16 v[50:53], v[182:185], v[190:193], v[50:53]
	v_mfma_f32_16x16x32_bf16 v[42:45], v[174:177], v[200:203], v[42:45]
	v_mfma_f32_16x16x32_bf16 v[34:37], v[182:185], v[200:203], v[34:37]
	v_mfma_f32_16x16x32_bf16 v[26:29], v[174:177], v[208:211], v[26:29]
	v_mfma_f32_16x16x32_bf16 v[18:21], v[182:185], v[208:211], v[18:21]
	v_mfma_f32_16x16x32_bf16 v[10:13], v[174:177], v[216:219], v[10:13]
	v_mfma_f32_16x16x32_bf16 v[2:5], v[182:185], v[216:219], v[2:5]
	s_setprio 0
	s_barrier
	s_add_i32 s64, 0, 0x18000
	v_add_u32_e32 v141, s64, v136
	s_add_i32 s65, 0, 0x1c000
	ds_read_b128 v[142:145], v141
	ds_read_b128 v[154:157], v141 offset:1024
	ds_read_b128 v[158:161], v141 offset:2048
	ds_read_b128 v[166:169], v141 offset:3072
	v_add_u32_e32 v141, s65, v136
	ds_read_b128 v[170:173], v141
	ds_read_b128 v[174:177], v141 offset:1024
	ds_read_b128 v[178:181], v141 offset:2048
	ds_read_b128 v[182:185], v141 offset:3072
	s_add_u32 s44, s44, 0x40000
	s_addc_u32 s45, s45, 0
	s_mov_b32 m0, s50
	v_lshl_add_u64 v[226:227], s[44:45], 0, v[146:147]
	ds_read_b128 v[186:189], v139 offset:32768
	ds_read_b128 v[190:193], v139 offset:33792
	ds_read_b128 v[194:197], v139 offset:34816
	ds_read_b128 v[200:203], v139 offset:35840
	ds_read_b128 v[204:207], v139 offset:36864
	ds_read_b128 v[208:211], v139 offset:37888
	ds_read_b128 v[212:215], v139 offset:38912
	ds_read_b128 v[216:219], v139 offset:39936
	global_load_lds_dwordx4 v[226:227], off
	v_lshl_add_u64 v[226:227], s[44:45], 0, v[150:151]
	s_mov_b32 m0, s51
	s_nop 0
	global_load_lds_dwordx4 v[226:227], off
	s_waitcnt vmcnt(8)
	s_waitcnt lgkmcnt(0)
	s_barrier
	s_setprio 1
	s_waitcnt lgkmcnt(0)
	v_mfma_f32_16x16x32_bf16 v[118:121], v[142:145], v[186:189], v[118:121]
	v_mfma_f32_16x16x32_bf16 v[114:117], v[158:161], v[186:189], v[114:117]
	v_mfma_f32_16x16x32_bf16 v[106:109], v[142:145], v[194:197], v[106:109]
	v_mfma_f32_16x16x32_bf16 v[102:105], v[158:161], v[194:197], v[102:105]
	v_mfma_f32_16x16x32_bf16 v[94:97], v[142:145], v[204:207], v[94:97]
	v_mfma_f32_16x16x32_bf16 v[86:89], v[158:161], v[204:207], v[86:89]
	v_mfma_f32_16x16x32_bf16 v[78:81], v[142:145], v[212:215], v[78:81]
	v_mfma_f32_16x16x32_bf16 v[70:73], v[158:161], v[212:215], v[70:73]
	v_mfma_f32_16x16x32_bf16 v[118:121], v[154:157], v[190:193], v[118:121]
	v_mfma_f32_16x16x32_bf16 v[114:117], v[166:169], v[190:193], v[114:117]
	v_mfma_f32_16x16x32_bf16 v[106:109], v[154:157], v[200:203], v[106:109]
	v_mfma_f32_16x16x32_bf16 v[102:105], v[166:169], v[200:203], v[102:105]
	v_mfma_f32_16x16x32_bf16 v[94:97], v[154:157], v[208:211], v[94:97]
	v_mfma_f32_16x16x32_bf16 v[86:89], v[166:169], v[208:211], v[86:89]
	v_mfma_f32_16x16x32_bf16 v[78:81], v[154:157], v[216:219], v[78:81]
	v_mfma_f32_16x16x32_bf16 v[70:73], v[166:169], v[216:219], v[70:73]
	s_setprio 0
	s_setprio 1
	v_mfma_f32_16x16x32_bf16 v[126:129], v[170:173], v[186:189], v[126:129]
	v_mfma_f32_16x16x32_bf16 v[122:125], v[178:181], v[186:189], v[122:125]
	v_mfma_f32_16x16x32_bf16 v[110:113], v[170:173], v[194:197], v[110:113]
	v_mfma_f32_16x16x32_bf16 v[98:101], v[178:181], v[194:197], v[98:101]
	v_mfma_f32_16x16x32_bf16 v[90:93], v[170:173], v[204:207], v[90:93]
	v_mfma_f32_16x16x32_bf16 v[82:85], v[178:181], v[204:207], v[82:85]
	v_mfma_f32_16x16x32_bf16 v[74:77], v[170:173], v[212:215], v[74:77]
	v_mfma_f32_16x16x32_bf16 v[66:69], v[178:181], v[212:215], v[66:69]
	v_mfma_f32_16x16x32_bf16 v[126:129], v[174:177], v[190:193], v[126:129]
	v_mfma_f32_16x16x32_bf16 v[122:125], v[182:185], v[190:193], v[122:125]
	v_mfma_f32_16x16x32_bf16 v[110:113], v[174:177], v[200:203], v[110:113]
	v_mfma_f32_16x16x32_bf16 v[98:101], v[182:185], v[200:203], v[98:101]
	v_mfma_f32_16x16x32_bf16 v[90:93], v[174:177], v[208:211], v[90:93]
	v_mfma_f32_16x16x32_bf16 v[82:85], v[182:185], v[208:211], v[82:85]
	v_mfma_f32_16x16x32_bf16 v[74:77], v[174:177], v[216:219], v[74:77]
	v_mfma_f32_16x16x32_bf16 v[66:69], v[182:185], v[216:219], v[66:69]
	s_setprio 0
	s_barrier
; #define PG8_STAGE(bufoff, gbase, voff) do { _Pragma("unroll") for (int _i = 0; _i < 2; ++_i) \
;         __builtin_amdgcn_global_load_lds((const unsigned*)((const char*)(gbase) + (voff)[_i]), (LAS unsigned*)(lds + (bufoff) + ldsw + _i * 8192), 16, 0, 0); } while (0)
; #define PG8_LDA(dst, b, h) do { _Pragma("unroll") for (int m = 0; m < 4; ++m) _Pragma("unroll") for (int k = 0; k < 2; ++k) dst[m][k] = *(const LAS bf16x8*)(lds + PG8_SA(b, h) + aoff + m * 2048 + k * 1024); } while (0)
; #define PG8_MMA(ai, bj, At, Bt) do { __builtin_amdgcn_s_setprio(1); _Pragma("unroll") for (int m = 0; m < 4; ++m) _Pragma("unroll") for (int n = 0; n < 2; ++n) _Pragma("unroll") for (int k = 0; k < 2; ++k) \
;         acc[ai][bj][m][n] = __builtin_amdgcn_mfma_f32_16x16x32_bf16(Bt[n][k], At[m][k], acc[ai][bj][m][n], 0, 0, 0); __builtin_amdgcn_s_setprio(0); } while (0)
; #define PG8_WAIT_V(n) asm volatile("s_waitcnt vmcnt(" #n ")" ::: "memory")
; #define PG8_WAIT_L(n) asm volatile("s_waitcnt lgkmcnt(" #n ")" ::: "memory")
; #define PG8_BAR __builtin_amdgcn_s_barrier()
; #define PG8_SCHED __builtin_amdgcn_sched_barrier(0)
;     __device__ __forceinline__ bool operator()(f32x4 (&acc)[2][2][4][2], const Unit& u, int wr, int wc, int fr, int fq) const {
;     ...
;         if (ssq) { const int hb = (u.half == 2) ? HALF : 0; float t8[8];
; #pragma unroll
;             for (int q = 0; q < 8; ++q) t8[q] = ssq[row0 + hb + (q >> 2) * HALF + (q & 3) * 16];
; __device__ __forceinline__ void gemm_phase(LAS unsigned char* lds, const Gemm g, const StaticOrder S, const Epi E) {
;     ...
;             PG8_WAIT_V(8); PG8_WAIT_L(0); PG8_BAR; PG8_MMA(0, 0, At, B0); PG8_MMA(0, 1, At, B1); PG8_BAR; PG8_SCHED;
;             if (full) PG8_LDA(At, 1, 1); PG8_STAGE(PG8_SB(1, 0), b3, voffB); PG8_STAGE(PG8_SB(1, 1), b3 + hstepB, voffB); PG8_STAGE(PG8_SA(1, 0), a3, voffA);
;             PG8_WAIT_V(8); PG8_WAIT_L(0); PG8_BAR; if (full) { PG8_MMA(1, 0, At, B0); PG8_MMA(1, 1, At, B1); } PG8_BAR; PG8_SCHED;
;         }
;         if (wr == 0) PG8_BAR;
	s_add_i32 s44, s64, s46
	v_lshl_add_u64 v[134:135], v[134:135], 0, s[16:17]
	s_mov_b32 m0, s44
	ds_read_b128 v[186:189], v139 offset:49152
	ds_read_b128 v[190:193], v139 offset:50176
	ds_read_b128 v[194:197], v139 offset:51200
	ds_read_b128 v[200:203], v139 offset:52224
	ds_read_b128 v[204:207], v139 offset:53248
	ds_read_b128 v[208:211], v139 offset:54272
	ds_read_b128 v[212:215], v139 offset:55296
	ds_read_b128 v[216:219], v139 offset:56320
	global_load_lds_dwordx4 v[134:135], off
	s_add_i32 m0, s44, 0x2000
	s_add_u32 s42, s42, 0x40080
	v_lshl_add_u64 v[134:135], v[220:221], 0, s[16:17]
	s_addc_u32 s43, s43, 0
	s_add_i32 s44, s65, s46
	global_load_lds_dwordx4 v[134:135], off
	v_lshl_add_u64 v[134:135], s[42:43], 0, v[148:149]
	s_mov_b32 m0, s44
	s_nop 0
	global_load_lds_dwordx4 v[134:135], off
	v_lshl_add_u64 v[134:135], s[42:43], 0, v[152:153]
	s_add_i32 m0, s44, 0x2000
	s_nop 0
	global_load_lds_dwordx4 v[134:135], off
	v_lshl_add_u64 v[134:135], v[222:223], 0, s[16:17]
	s_mov_b32 m0, s55
	s_nop 0
	global_load_lds_dwordx4 v[134:135], off
	v_lshl_add_u64 v[134:135], v[224:225], 0, s[16:17]
	s_mov_b32 m0, s56
	s_nop 0
	global_load_lds_dwordx4 v[134:135], off
	s_waitcnt vmcnt(8)
	s_waitcnt lgkmcnt(0)
	s_barrier
	s_setprio 1
	s_waitcnt lgkmcnt(0)
	v_mfma_f32_16x16x32_bf16 v[62:65], v[142:145], v[186:189], v[62:65]
	v_mfma_f32_16x16x32_bf16 v[54:57], v[158:161], v[186:189], v[54:57]
	v_mfma_f32_16x16x32_bf16 v[46:49], v[142:145], v[194:197], v[46:49]
	v_mfma_f32_16x16x32_bf16 v[38:41], v[158:161], v[194:197], v[38:41]
	v_mfma_f32_16x16x32_bf16 v[30:33], v[142:145], v[204:207], v[30:33]
	v_mfma_f32_16x16x32_bf16 v[22:25], v[158:161], v[204:207], v[22:25]
	v_mfma_f32_16x16x32_bf16 v[14:17], v[142:145], v[212:215], v[14:17]
	v_mfma_f32_16x16x32_bf16 v[6:9], v[158:161], v[212:215], v[6:9]
	v_mfma_f32_16x16x32_bf16 v[62:65], v[154:157], v[190:193], v[62:65]
	v_mfma_f32_16x16x32_bf16 v[54:57], v[166:169], v[190:193], v[54:57]
	v_mfma_f32_16x16x32_bf16 v[46:49], v[154:157], v[200:203], v[46:49]
	v_mfma_f32_16x16x32_bf16 v[38:41], v[166:169], v[200:203], v[38:41]
	v_mfma_f32_16x16x32_bf16 v[30:33], v[154:157], v[208:211], v[30:33]
	v_mfma_f32_16x16x32_bf16 v[22:25], v[166:169], v[208:211], v[22:25]
	v_mfma_f32_16x16x32_bf16 v[14:17], v[154:157], v[216:219], v[14:17]
	v_mfma_f32_16x16x32_bf16 v[6:9], v[166:169], v[216:219], v[6:9]
	s_setprio 0
	s_setprio 1
	v_mfma_f32_16x16x32_bf16 v[58:61], v[170:173], v[186:189], v[58:61]
	v_mfma_f32_16x16x32_bf16 v[50:53], v[178:181], v[186:189], v[50:53]
	v_mfma_f32_16x16x32_bf16 v[42:45], v[170:173], v[194:197], v[42:45]
	v_mfma_f32_16x16x32_bf16 v[34:37], v[178:181], v[194:197], v[34:37]
	v_mfma_f32_16x16x32_bf16 v[26:29], v[170:173], v[204:207], v[26:29]
	v_mfma_f32_16x16x32_bf16 v[18:21], v[178:181], v[204:207], v[18:21]
	v_mfma_f32_16x16x32_bf16 v[10:13], v[170:173], v[212:215], v[10:13]
	v_mfma_f32_16x16x32_bf16 v[2:5], v[178:181], v[212:215], v[2:5]
	v_mfma_f32_16x16x32_bf16 v[58:61], v[174:177], v[190:193], v[58:61]
	v_mfma_f32_16x16x32_bf16 v[50:53], v[182:185], v[190:193], v[50:53]
	v_mfma_f32_16x16x32_bf16 v[42:45], v[174:177], v[200:203], v[42:45]
	v_mfma_f32_16x16x32_bf16 v[34:37], v[182:185], v[200:203], v[34:37]
	v_mfma_f32_16x16x32_bf16 v[26:29], v[174:177], v[208:211], v[26:29]
	v_mfma_f32_16x16x32_bf16 v[18:21], v[182:185], v[208:211], v[18:21]
	v_mfma_f32_16x16x32_bf16 v[10:13], v[174:177], v[216:219], v[10:13]
	v_mfma_f32_16x16x32_bf16 v[2:5], v[182:185], v[216:219], v[2:5]
	s_setprio 0
	s_barrier
	s_add_i32 s63, s63, 2
	s_add_u32 s23, s23, 0x100
	s_addc_u32 s25, s25, 0
	s_add_u32 s40, s40, 0x100
	s_addc_u32 s41, s41, 0
	s_cmp_gt_u32 s63, 13
	s_cbranch_scc0 .LBB0_305
	s_lshl_b32 s23, s38, 8
	s_add_i32 s23, s23, s53
	v_add_u32_e32 v134, s23, v163
	v_ashrrev_i32_e32 v135, 31, v134
	v_lshl_add_u64 v[142:143], v[134:135], 2, s[14:15]
	global_load_dword v135, v[142:143], off
	global_load_dword v158, v[142:143], off offset:64
	global_load_dword v159, v[142:143], off offset:128
	global_load_dword v160, v[142:143], off offset:192
	global_load_dword v141, v[142:143], off offset:512
	global_load_dword v161, v[142:143], off offset:576
	global_load_dword v165, v[142:143], off offset:640
	global_load_dword v166, v[142:143], off offset:704
	s_and_b64 vcc, exec, s[18:19]
	s_cbranch_vccz .LBB0_308
	s_barrier
; __device__ __forceinline__ unsigned cvt_pk_bf16(float lo, float hi) { f32x2 v = {lo, hi}; bf2_t b = __builtin_convertvector(v, bf2_t); return __builtin_bit_cast(unsigned, b); }
;     __device__ __forceinline__ bool operator()(f32x4 (&acc)[2][2][4][2], const Unit& u, int wr, int wc, int fr, int fq) const {
;     ...
;             for (int q = 0; q < 8; ++q) ri8[q] = __builtin_amdgcn_rsqf(t8[q] * (1.0f / D) + EPS);
;     ...
;         if (mode == M_SWIGLU) {
;             const int col0 = u.pn * HALF + wc * 32 + 8 * fq; const int nai = u.half ? 1 : 2, hoff = (u.half == 2) ? HALF : 0;
; #pragma unroll
;             for (int ai = 0; ai < 2; ++ai) if (ai < nai)
; #pragma unroll
;                 for (int m = 0; m < 4; ++m) { const int row = row0 + hoff + ai * HALF + m * 16; const float ri = ri8[4 * ai + m];
;                     float o[8];
; #pragma unroll
;                     for (int n = 0; n < 2; ++n)
; #pragma unroll
;                         for (int j = 0; j < 4; ++j) { const float c1 = acc[ai][0][m][n][j], c3 = acc[ai][1][m][n][j]; o[4 * n + j] = (c1 * c3) * (ri * ri) * __builtin_amdgcn_rcpf(1.f + __builtin_amdgcn_exp2f(c1 * (ri * -1.4426950408889634f))); }
;                     u32x4 w; w.x = cvt_pk_bf16(o[0], o[1]); w.y = cvt_pk_bf16(o[2], o[3]); w.z = cvt_pk_bf16(o[4], o[5]); w.w = cvt_pk_bf16(o[6], o[7]);
;                     *(u32x4*)(O + (size_t)row * ldc + col0) = w; }
.LBB0_308:
	s_lshl_b32 s23, s62, 7
	s_or_b32 s23, s23, s54
	v_pk_mul_f32 v[154:155], v[110:111], v[106:107]
	v_lshl_add_u32 v110, v164, 3, s23
	v_pk_mul_f32 v[144:145], v[122:123], v[114:115]
	v_mov_b64_e32 v[122:123], s[20:21]
	v_ashrrev_i32_e32 v111, 31, v110
	v_mad_i64_i32 v[156:157], s[40:41], v134, s68, v[122:123]
	v_lshlrev_b64 v[110:111], 1, v[110:111]
	v_lshl_add_u64 v[142:143], v[156:157], 0, v[110:111]
	v_pk_mul_f32 v[128:129], v[128:129], v[120:121]
	v_pk_mul_f32 v[126:127], v[126:127], v[118:119]
	v_pk_mul_f32 v[124:125], v[124:125], v[116:117]
	v_pk_mul_f32 v[112:113], v[112:113], v[108:109]
	v_pk_mul_f32 v[100:101], v[100:101], v[104:105]
	v_pk_mul_f32 v[98:99], v[98:99], v[102:103]
	v_pk_mul_f32 v[90:91], v[90:91], v[94:95]
	v_pk_mul_f32 v[92:93], v[92:93], v[96:97]
	v_pk_mul_f32 v[84:85], v[84:85], v[88:89]
	v_pk_mul_f32 v[82:83], v[82:83], v[86:87]
	v_pk_mul_f32 v[74:75], v[74:75], v[78:79]
	v_pk_mul_f32 v[76:77], v[76:77], v[80:81]
	v_pk_mul_f32 v[68:69], v[68:69], v[72:73]
	v_pk_mul_f32 v[66:67], v[66:67], v[70:71]
	v_pk_mul_f32 v[58:59], v[58:59], v[62:63]
	v_pk_mul_f32 v[60:61], v[60:61], v[64:65]
	v_pk_mul_f32 v[52:53], v[52:53], v[56:57]
	v_pk_mul_f32 v[50:51], v[50:51], v[54:55]
	v_pk_mul_f32 v[42:43], v[42:43], v[46:47]
	v_pk_mul_f32 v[44:45], v[44:45], v[48:49]
	v_pk_mul_f32 v[36:37], v[36:37], v[40:41]
	v_pk_mul_f32 v[34:35], v[34:35], v[38:39]
	v_pk_mul_f32 v[26:27], v[26:27], v[30:31]
	v_pk_mul_f32 v[28:29], v[28:29], v[32:33]
	v_pk_mul_f32 v[20:21], v[20:21], v[24:25]
	v_pk_mul_f32 v[18:19], v[18:19], v[22:23]
	v_pk_mul_f32 v[10:11], v[10:11], v[14:15]
	v_pk_mul_f32 v[12:13], v[12:13], v[16:17]
	v_pk_mul_f32 v[4:5], v[4:5], v[8:9]
	v_pk_mul_f32 v[2:3], v[2:3], v[6:7]
	s_andn2_b64 vcc, exec, s[2:3]
	s_mov_b64 s[2:3], -1
	s_waitcnt vmcnt(0)
	v_fmamk_f32 v135, v135, 0x3a800000, v140
	v_fmamk_f32 v156, v158, 0x3a800000, v140
	v_fmamk_f32 v157, v159, 0x3a800000, v140
	v_rsq_f32_e32 v135, v135
	v_rsq_f32_e32 v159, v156
	v_rsq_f32_e32 v157, v157
	v_fmamk_f32 v158, v160, 0x3a800000, v140
	v_mul_f32_e32 v156, v135, v135
	v_mul_f32_e32 v135, 0xbfb8aa3b, v135
	v_rsq_f32_e32 v160, v158
	v_mul_f32_e32 v158, v159, v159
	v_mul_f32_e32 v159, 0xbfb8aa3b, v159
	v_mul_f32_e32 v167, v118, v135
	v_mul_f32_e32 v168, v119, v135
	v_pk_mul_f32 v[118:119], v[126:127], v[156:157] op_sel_hi:[1,0]
	v_mul_f32_e32 v126, v120, v135
	v_mul_f32_e32 v127, v121, v135
	v_pk_mul_f32 v[120:121], v[128:129], v[156:157] op_sel_hi:[1,0]
	v_mul_f32_e32 v128, v114, v135
	v_mul_f32_e32 v129, v115, v135
	v_pk_mul_f32 v[114:115], v[144:145], v[156:157] op_sel_hi:[1,0]
	v_mul_f32_e32 v144, v116, v135
	v_mul_f32_e32 v135, v117, v135
	v_pk_mul_f32 v[116:117], v[124:125], v[156:157] op_sel_hi:[1,0]
	v_mul_f32_e32 v124, v106, v159
	v_mul_f32_e32 v125, v107, v159
	v_pk_mul_f32 v[106:107], v[154:155], v[158:159] op_sel_hi:[1,0]
	v_mul_f32_e32 v108, v108, v159
	v_mul_f32_e32 v109, v109, v159
	v_exp_f32_e32 v145, v167
	v_exp_f32_e32 v154, v168
	v_exp_f32_e32 v126, v126
	v_exp_f32_e32 v127, v127
	v_exp_f32_e32 v128, v128
	v_exp_f32_e32 v129, v129
	v_exp_f32_e32 v144, v144
	v_exp_f32_e32 v135, v135
	v_exp_f32_e32 v124, v124
	v_exp_f32_e32 v125, v125
	v_exp_f32_e32 v108, v108
	v_exp_f32_e32 v109, v109
	v_add_f32_e32 v145, 1.0, v145
	v_add_f32_e32 v154, 1.0, v154
	v_add_f32_e32 v126, 1.0, v126
	v_add_f32_e32 v127, 1.0, v127
	v_add_f32_e32 v128, 1.0, v128
	v_add_f32_e32 v129, 1.0, v129
	v_add_f32_e32 v144, 1.0, v144
	v_add_f32_e32 v135, 1.0, v135
	v_add_f32_e32 v155, 1.0, v124
	v_add_f32_e32 v156, 1.0, v125
	v_add_f32_e32 v167, 1.0, v108
	v_add_f32_e32 v168, 1.0, v109
	v_rcp_f32_e32 v108, v145
	v_rcp_f32_e32 v109, v154
	v_rcp_f32_e32 v124, v126
	v_rcp_f32_e32 v125, v127
	v_rcp_f32_e32 v126, v128
	v_rcp_f32_e32 v127, v129
	v_rcp_f32_e32 v128, v144
	v_rcp_f32_e32 v129, v135
	v_rcp_f32_e32 v144, v155
	v_rcp_f32_e32 v145, v156
	v_pk_mul_f32 v[108:109], v[118:119], v[108:109]
	v_pk_mul_f32 v[118:119], v[120:121], v[124:125]
	v_pk_mul_f32 v[114:115], v[114:115], v[126:127]
	v_pk_mul_f32 v[116:117], v[116:117], v[128:129]
	v_pk_mul_f32 v[120:121], v[106:107], v[144:145]
	v_cvt_pk_bf16_f32 v106, v108, v109
	v_cvt_pk_bf16_f32 v107, v118, v119
	v_cvt_pk_bf16_f32 v108, v114, v115
	v_cvt_pk_bf16_f32 v109, v116, v117
	global_store_dwordx4 v[142:143], v[106:109], off
	v_mul_f32_e32 v104, v104, v159
	v_mul_f32_e32 v105, v105, v159
	v_mul_f32_e32 v108, v102, v159
	v_mul_f32_e32 v109, v103, v159
	v_exp_f32_e32 v108, v108
	v_exp_f32_e32 v109, v109
	v_exp_f32_e32 v104, v104
	v_exp_f32_e32 v105, v105
	v_add_f32_e32 v108, 1.0, v108
	v_add_f32_e32 v109, 1.0, v109
	v_rcp_f32_e32 v108, v108
	v_rcp_f32_e32 v109, v109
	v_add_f32_e32 v102, 1.0, v104
	v_add_f32_e32 v103, 1.0, v105
	v_rcp_f32_e32 v102, v102
	v_rcp_f32_e32 v103, v103
	v_rcp_f32_e32 v154, v167
	v_rcp_f32_e32 v155, v168
	v_pk_mul_f32 v[98:99], v[98:99], v[158:159] op_sel_hi:[1,0]
	v_pk_mul_f32 v[106:107], v[112:113], v[158:159] op_sel_hi:[1,0]
	v_pk_mul_f32 v[104:105], v[98:99], v[108:109]
	v_pk_mul_f32 v[98:99], v[100:101], v[158:159] op_sel_hi:[1,0]
	v_add_u32_e32 v108, 16, v134
	v_pk_mul_f32 v[102:103], v[98:99], v[102:103]
	v_pk_mul_f32 v[106:107], v[106:107], v[154:155]
	v_cvt_pk_bf16_f32 v101, v102, v103
	v_mad_i64_i32 v[102:103], s[40:41], v108, s68, v[122:123]
	v_cvt_pk_bf16_f32 v98, v120, v121
	v_cvt_pk_bf16_f32 v99, v106, v107
	v_cvt_pk_bf16_f32 v100, v104, v105
	v_lshl_add_u64 v[102:103], v[102:103], 0, v[110:111]
	global_store_dwordx4 v[102:103], v[98:101], off
	s_nop 1
	v_mul_f32_e32 v99, 0xbfb8aa3b, v157
	v_mul_f32_e32 v98, v94, v99
	v_exp_f32_e32 v100, v98
	v_mul_f32_e32 v98, v95, v99
	v_mul_f32_e32 v94, v96, v99
; __device__ __forceinline__ unsigned cvt_pk_bf16(float lo, float hi) { f32x2 v = {lo, hi}; bf2_t b = __builtin_convertvector(v, bf2_t); return __builtin_bit_cast(unsigned, b); }
;     __device__ __forceinline__ bool operator()(f32x4 (&acc)[2][2][4][2], const Unit& u, int wr, int wc, int fr, int fq) const {
;     ...
;             for (int q = 0; q < 8; ++q) ri8[q] = __builtin_amdgcn_rsqf(t8[q] * (1.0f / D) + EPS);
;     ...
;                 for (int m = 0; m < 4; ++m) { const int row = row0 + hoff + ai * HALF + m * 16; const float ri = ri8[4 * ai + m];
;                     float o[8];
; #pragma unroll
;                     for (int n = 0; n < 2; ++n)
; #pragma unroll
;                         for (int j = 0; j < 4; ++j) { const float c1 = acc[ai][0][m][n][j], c3 = acc[ai][1][m][n][j]; o[4 * n + j] = (c1 * c3) * (ri * ri) * __builtin_amdgcn_rcpf(1.f + __builtin_amdgcn_exp2f(c1 * (ri * -1.4426950408889634f))); }
;                     u32x4 w; w.x = cvt_pk_bf16(o[0], o[1]); w.y = cvt_pk_bf16(o[2], o[3]); w.z = cvt_pk_bf16(o[4], o[5]); w.w = cvt_pk_bf16(o[6], o[7]);
;                     *(u32x4*)(O + (size_t)row * ldc + col0) = w; }
	v_mul_f32_e32 v95, v97, v99
	v_exp_f32_e32 v94, v94
	v_exp_f32_e32 v95, v95
	v_mul_f32_e32 v96, v86, v99
	v_mul_f32_e32 v97, v87, v99
	v_add_f32_e32 v94, 1.0, v94
	v_add_f32_e32 v95, 1.0, v95
	v_rcp_f32_e32 v94, v94
	v_rcp_f32_e32 v95, v95
	v_exp_f32_e32 v96, v96
	v_exp_f32_e32 v97, v97
	v_mul_f32_e32 v88, v88, v99
	v_mul_f32_e32 v89, v89, v99
	v_exp_f32_e32 v88, v88
	v_exp_f32_e32 v89, v89
	v_exp_f32_e32 v101, v98
	v_mul_f32_e32 v98, v157, v157
	v_pk_mul_f32 v[92:93], v[92:93], v[98:99] op_sel_hi:[1,0]
	v_add_f32_e32 v86, 1.0, v88
	v_pk_mul_f32 v[92:93], v[92:93], v[94:95]
	v_add_f32_e32 v94, 1.0, v96
	v_add_f32_e32 v95, 1.0, v97
	v_rcp_f32_e32 v94, v94
	v_rcp_f32_e32 v95, v95
	v_add_f32_e32 v87, 1.0, v89
	v_add_f32_e32 v100, 1.0, v100
	v_add_f32_e32 v101, 1.0, v101
	v_rcp_f32_e32 v86, v86
	v_rcp_f32_e32 v87, v87
	v_rcp_f32_e32 v100, v100
	v_rcp_f32_e32 v101, v101
	v_pk_mul_f32 v[82:83], v[82:83], v[98:99] op_sel_hi:[1,0]
	v_pk_mul_f32 v[90:91], v[90:91], v[98:99] op_sel_hi:[1,0]
	v_pk_mul_f32 v[88:89], v[82:83], v[94:95]
	v_pk_mul_f32 v[82:83], v[84:85], v[98:99] op_sel_hi:[1,0]
	v_add_u32_e32 v94, 32, v134
	v_pk_mul_f32 v[86:87], v[82:83], v[86:87]
	v_pk_mul_f32 v[90:91], v[90:91], v[100:101]
	v_cvt_pk_bf16_f32 v85, v86, v87
	v_mad_i64_i32 v[86:87], s[40:41], v94, s68, v[122:123]
	v_cvt_pk_bf16_f32 v82, v90, v91
	v_cvt_pk_bf16_f32 v83, v92, v93
	v_cvt_pk_bf16_f32 v84, v88, v89
	v_lshl_add_u64 v[86:87], v[86:87], 0, v[110:111]
	global_store_dwordx4 v[86:87], v[82:85], off
	s_nop 1
	v_mul_f32_e32 v83, 0xbfb8aa3b, v160
	v_mul_f32_e32 v82, v78, v83
	v_exp_f32_e32 v84, v82
	v_mul_f32_e32 v82, v79, v83
	v_mul_f32_e32 v78, v80, v83
	v_mul_f32_e32 v79, v81, v83
	v_exp_f32_e32 v78, v78
	v_exp_f32_e32 v79, v79
	v_mul_f32_e32 v80, v70, v83
	v_mul_f32_e32 v81, v71, v83
	v_add_f32_e32 v78, 1.0, v78
	v_add_f32_e32 v79, 1.0, v79
	v_rcp_f32_e32 v78, v78
	v_rcp_f32_e32 v79, v79
	v_exp_f32_e32 v80, v80
	v_exp_f32_e32 v81, v81
	v_mul_f32_e32 v72, v72, v83
	v_mul_f32_e32 v73, v73, v83
	v_exp_f32_e32 v72, v72
	v_exp_f32_e32 v73, v73
	v_exp_f32_e32 v85, v82
	v_mul_f32_e32 v82, v160, v160
	v_pk_mul_f32 v[76:77], v[76:77], v[82:83] op_sel_hi:[1,0]
	v_add_f32_e32 v70, 1.0, v72
	v_pk_mul_f32 v[76:77], v[76:77], v[78:79]
	v_add_f32_e32 v78, 1.0, v80
	v_add_f32_e32 v79, 1.0, v81
	v_rcp_f32_e32 v78, v78
	v_rcp_f32_e32 v79, v79
	v_add_f32_e32 v71, 1.0, v73
	v_add_f32_e32 v84, 1.0, v84
	v_add_f32_e32 v85, 1.0, v85
	v_rcp_f32_e32 v70, v70
	v_rcp_f32_e32 v71, v71
	v_rcp_f32_e32 v84, v84
	v_rcp_f32_e32 v85, v85
	v_pk_mul_f32 v[66:67], v[66:67], v[82:83] op_sel_hi:[1,0]
	v_pk_mul_f32 v[74:75], v[74:75], v[82:83] op_sel_hi:[1,0]
	v_pk_mul_f32 v[72:73], v[66:67], v[78:79]
	v_pk_mul_f32 v[66:67], v[68:69], v[82:83] op_sel_hi:[1,0]
	v_add_u32_e32 v78, 48, v134
	v_pk_mul_f32 v[70:71], v[66:67], v[70:71]
	v_pk_mul_f32 v[74:75], v[74:75], v[84:85]
	v_cvt_pk_bf16_f32 v69, v70, v71
	v_mad_i64_i32 v[70:71], s[40:41], v78, s68, v[122:123]
	v_cvt_pk_bf16_f32 v66, v74, v75
	v_cvt_pk_bf16_f32 v67, v76, v77
	v_cvt_pk_bf16_f32 v68, v72, v73
	v_lshl_add_u64 v[70:71], v[70:71], 0, v[110:111]
	global_store_dwordx4 v[70:71], v[66:69], off
	v_add_u32_e32 v72, 0x80, v134
	s_nop 0
	v_fmamk_f32 v66, v141, 0x3a800000, v140
	v_rsq_f32_e32 v66, v66
	v_fmamk_f32 v68, v165, 0x3a800000, v140
	v_rsq_f32_e32 v70, v68
	v_fmamk_f32 v68, v166, 0x3a800000, v140
	v_mul_f32_e32 v73, 0xbfb8aa3b, v66
	v_rsq_f32_e32 v71, v68
	v_mul_f32_e32 v68, v62, v73
	v_mul_f32_e32 v69, v63, v73
	v_mul_f32_e32 v62, v64, v73
	v_mul_f32_e32 v63, v65, v73
	v_exp_f32_e32 v62, v62
	v_exp_f32_e32 v63, v63
	v_fmamk_f32 v67, v161, 0x3a800000, v140
	v_rsq_f32_e32 v67, v67
	v_add_f32_e32 v62, 1.0, v62
	v_add_f32_e32 v63, 1.0, v63
	v_mul_f32_e32 v64, v54, v73
	v_mul_f32_e32 v65, v55, v73
	v_rcp_f32_e32 v62, v62
	v_rcp_f32_e32 v63, v63
	v_exp_f32_e32 v64, v64
	v_exp_f32_e32 v65, v65
	v_mul_f32_e32 v56, v56, v73
	v_mul_f32_e32 v57, v57, v73
	v_exp_f32_e32 v56, v56
	v_exp_f32_e32 v57, v57
	v_exp_f32_e32 v68, v68
	v_exp_f32_e32 v69, v69
	v_mul_f32_e32 v66, v66, v66
	v_pk_mul_f32 v[60:61], v[60:61], v[66:67] op_sel_hi:[1,0]
	v_add_f32_e32 v54, 1.0, v56
	v_pk_mul_f32 v[60:61], v[60:61], v[62:63]
	v_add_f32_e32 v62, 1.0, v64
	v_add_f32_e32 v63, 1.0, v65
	v_rcp_f32_e32 v62, v62
	v_rcp_f32_e32 v63, v63
	v_add_f32_e32 v55, 1.0, v57
	v_add_f32_e32 v68, 1.0, v68
	v_add_f32_e32 v69, 1.0, v69
	v_rcp_f32_e32 v54, v54
	v_rcp_f32_e32 v55, v55
	v_rcp_f32_e32 v68, v68
	v_rcp_f32_e32 v69, v69
	v_pk_mul_f32 v[50:51], v[50:51], v[66:67] op_sel_hi:[1,0]
	v_pk_mul_f32 v[58:59], v[58:59], v[66:67] op_sel_hi:[1,0]
	v_pk_mul_f32 v[56:57], v[50:51], v[62:63]
	v_pk_mul_f32 v[50:51], v[52:53], v[66:67] op_sel_hi:[1,0]
	v_pk_mul_f32 v[58:59], v[58:59], v[68:69]
	v_pk_mul_f32 v[54:55], v[50:51], v[54:55]
	v_cvt_pk_bf16_f32 v50, v58, v59
	v_cvt_pk_bf16_f32 v53, v54, v55
	v_mad_i64_i32 v[54:55], s[40:41], v72, s68, v[122:123]
	v_cvt_pk_bf16_f32 v51, v60, v61
	v_cvt_pk_bf16_f32 v52, v56, v57
	v_lshl_add_u64 v[54:55], v[54:55], 0, v[110:111]
; __device__ __forceinline__ unsigned cvt_pk_bf16(float lo, float hi) { f32x2 v = {lo, hi}; bf2_t b = __builtin_convertvector(v, bf2_t); return __builtin_bit_cast(unsigned, b); }
; #define PG8_BAR __builtin_amdgcn_s_barrier()
;     __device__ __forceinline__ bool operator()(f32x4 (&acc)[2][2][4][2], const Unit& u, int wr, int wc, int fr, int fq) const {
;     ...
;                 for (int m = 0; m < 4; ++m) { const int row = row0 + hoff + ai * HALF + m * 16; const float ri = ri8[4 * ai + m];
;                     float o[8];
; #pragma unroll
;                     for (int n = 0; n < 2; ++n)
; #pragma unroll
;                         for (int j = 0; j < 4; ++j) { const float c1 = acc[ai][0][m][n][j], c3 = acc[ai][1][m][n][j]; o[4 * n + j] = (c1 * c3) * (ri * ri) * __builtin_amdgcn_rcpf(1.f + __builtin_amdgcn_exp2f(c1 * (ri * -1.4426950408889634f))); }
;                     u32x4 w; w.x = cvt_pk_bf16(o[0], o[1]); w.y = cvt_pk_bf16(o[2], o[3]); w.z = cvt_pk_bf16(o[4], o[5]); w.w = cvt_pk_bf16(o[6], o[7]);
;                     *(u32x4*)(O + (size_t)row * ldc + col0) = w; }
; __device__ __forceinline__ void gemm_phase(LAS unsigned char* lds, const Gemm g, const StaticOrder S, const Epi E) {
;     ...
;         if (nxt.seg == 0) ++ui;
;         cur = nxt; cA = nA; cB = nB;
;         if (wr == 1) PG8_BAR;
	global_store_dwordx4 v[54:55], v[50:53], off
	s_nop 1
	v_mul_f32_e32 v51, 0xbfb8aa3b, v67
	v_mul_f32_e32 v50, v46, v51
	v_exp_f32_e32 v52, v50
	v_mul_f32_e32 v50, v47, v51
	v_mul_f32_e32 v46, v48, v51
	v_mul_f32_e32 v47, v49, v51
	v_exp_f32_e32 v46, v46
	v_exp_f32_e32 v47, v47
	v_mul_f32_e32 v48, v38, v51
	v_mul_f32_e32 v49, v39, v51
	v_add_f32_e32 v46, 1.0, v46
	v_add_f32_e32 v47, 1.0, v47
	v_rcp_f32_e32 v46, v46
	v_rcp_f32_e32 v47, v47
	v_exp_f32_e32 v48, v48
	v_exp_f32_e32 v49, v49
	v_mul_f32_e32 v40, v40, v51
	v_mul_f32_e32 v41, v41, v51
	v_exp_f32_e32 v40, v40
	v_exp_f32_e32 v41, v41
	v_exp_f32_e32 v53, v50
	v_mul_f32_e32 v50, v67, v67
	v_pk_mul_f32 v[44:45], v[44:45], v[50:51] op_sel_hi:[1,0]
	v_add_f32_e32 v38, 1.0, v40
	v_pk_mul_f32 v[44:45], v[44:45], v[46:47]
	v_add_f32_e32 v46, 1.0, v48
	v_add_f32_e32 v47, 1.0, v49
	v_rcp_f32_e32 v46, v46
	v_rcp_f32_e32 v47, v47
	v_add_f32_e32 v39, 1.0, v41
	v_add_f32_e32 v52, 1.0, v52
	v_add_f32_e32 v53, 1.0, v53
	v_rcp_f32_e32 v38, v38
	v_rcp_f32_e32 v39, v39
	v_rcp_f32_e32 v52, v52
	v_rcp_f32_e32 v53, v53
	v_pk_mul_f32 v[34:35], v[34:35], v[50:51] op_sel_hi:[1,0]
	v_pk_mul_f32 v[42:43], v[42:43], v[50:51] op_sel_hi:[1,0]
	v_pk_mul_f32 v[40:41], v[34:35], v[46:47]
	v_pk_mul_f32 v[34:35], v[36:37], v[50:51] op_sel_hi:[1,0]
	v_add_u32_e32 v46, 0x90, v134
	v_pk_mul_f32 v[38:39], v[34:35], v[38:39]
	v_pk_mul_f32 v[42:43], v[42:43], v[52:53]
	v_cvt_pk_bf16_f32 v37, v38, v39
	v_mad_i64_i32 v[38:39], s[40:41], v46, s68, v[122:123]
	v_cvt_pk_bf16_f32 v34, v42, v43
	v_cvt_pk_bf16_f32 v35, v44, v45
	v_cvt_pk_bf16_f32 v36, v40, v41
	v_lshl_add_u64 v[38:39], v[38:39], 0, v[110:111]
	global_store_dwordx4 v[38:39], v[34:37], off
	s_nop 1
	v_mul_f32_e32 v35, 0xbfb8aa3b, v70
	v_mul_f32_e32 v34, v30, v35
	v_exp_f32_e32 v36, v34
	v_mul_f32_e32 v34, v31, v35
	v_mul_f32_e32 v30, v32, v35
	v_mul_f32_e32 v31, v33, v35
	v_exp_f32_e32 v30, v30
	v_exp_f32_e32 v31, v31
	v_mul_f32_e32 v32, v22, v35
	v_mul_f32_e32 v33, v23, v35
	v_add_f32_e32 v30, 1.0, v30
	v_add_f32_e32 v31, 1.0, v31
	v_rcp_f32_e32 v30, v30
	v_rcp_f32_e32 v31, v31
	v_exp_f32_e32 v32, v32
	v_exp_f32_e32 v33, v33
	v_mul_f32_e32 v24, v24, v35
	v_mul_f32_e32 v25, v25, v35
	v_exp_f32_e32 v24, v24
	v_exp_f32_e32 v25, v25
	v_exp_f32_e32 v37, v34
	v_mul_f32_e32 v34, v70, v70
	v_pk_mul_f32 v[28:29], v[28:29], v[34:35] op_sel_hi:[1,0]
	v_add_f32_e32 v22, 1.0, v24
	v_pk_mul_f32 v[28:29], v[28:29], v[30:31]
	v_add_f32_e32 v30, 1.0, v32
	v_add_f32_e32 v31, 1.0, v33
	v_rcp_f32_e32 v30, v30
	v_rcp_f32_e32 v31, v31
	v_add_f32_e32 v23, 1.0, v25
	v_add_f32_e32 v36, 1.0, v36
	v_add_f32_e32 v37, 1.0, v37
	v_rcp_f32_e32 v22, v22
	v_rcp_f32_e32 v23, v23
	v_rcp_f32_e32 v36, v36
	v_rcp_f32_e32 v37, v37
	v_pk_mul_f32 v[18:19], v[18:19], v[34:35] op_sel_hi:[1,0]
	v_pk_mul_f32 v[26:27], v[26:27], v[34:35] op_sel_hi:[1,0]
	v_pk_mul_f32 v[24:25], v[18:19], v[30:31]
	v_pk_mul_f32 v[18:19], v[20:21], v[34:35] op_sel_hi:[1,0]
	v_add_u32_e32 v30, 0xa0, v134
	v_pk_mul_f32 v[22:23], v[18:19], v[22:23]
	v_pk_mul_f32 v[26:27], v[26:27], v[36:37]
	v_cvt_pk_bf16_f32 v21, v22, v23
	v_mad_i64_i32 v[22:23], s[40:41], v30, s68, v[122:123]
	v_cvt_pk_bf16_f32 v18, v26, v27
	v_cvt_pk_bf16_f32 v19, v28, v29
	v_cvt_pk_bf16_f32 v20, v24, v25
	v_lshl_add_u64 v[22:23], v[22:23], 0, v[110:111]
	global_store_dwordx4 v[22:23], v[18:21], off
	s_nop 1
	v_mul_f32_e32 v19, 0xbfb8aa3b, v71
	v_mul_f32_e32 v18, v14, v19
	v_exp_f32_e32 v20, v18
	v_mul_f32_e32 v18, v15, v19
	v_mul_f32_e32 v14, v16, v19
	v_mul_f32_e32 v15, v17, v19
	v_exp_f32_e32 v14, v14
	v_exp_f32_e32 v15, v15
	v_mul_f32_e32 v16, v6, v19
	v_mul_f32_e32 v17, v7, v19
	v_add_f32_e32 v14, 1.0, v14
	v_add_f32_e32 v15, 1.0, v15
	v_rcp_f32_e32 v14, v14
	v_rcp_f32_e32 v15, v15
	v_exp_f32_e32 v16, v16
	v_exp_f32_e32 v17, v17
	v_mul_f32_e32 v8, v8, v19
	v_mul_f32_e32 v9, v9, v19
	v_exp_f32_e32 v8, v8
	v_exp_f32_e32 v9, v9
	v_exp_f32_e32 v21, v18
	v_mul_f32_e32 v18, v71, v71
	v_pk_mul_f32 v[12:13], v[12:13], v[18:19] op_sel_hi:[1,0]
	v_add_f32_e32 v6, 1.0, v8
	v_pk_mul_f32 v[12:13], v[12:13], v[14:15]
	v_add_f32_e32 v14, 1.0, v16
	v_add_f32_e32 v15, 1.0, v17
	v_rcp_f32_e32 v14, v14
	v_rcp_f32_e32 v15, v15
	v_add_f32_e32 v7, 1.0, v9
	v_add_f32_e32 v20, 1.0, v20
	v_add_f32_e32 v21, 1.0, v21
	v_rcp_f32_e32 v6, v6
	v_rcp_f32_e32 v7, v7
	v_rcp_f32_e32 v20, v20
	v_rcp_f32_e32 v21, v21
	v_pk_mul_f32 v[2:3], v[2:3], v[18:19] op_sel_hi:[1,0]
	v_pk_mul_f32 v[10:11], v[10:11], v[18:19] op_sel_hi:[1,0]
	v_pk_mul_f32 v[8:9], v[2:3], v[14:15]
	v_pk_mul_f32 v[2:3], v[4:5], v[18:19] op_sel_hi:[1,0]
	v_add_u32_e32 v14, 0xb0, v134
	v_pk_mul_f32 v[6:7], v[2:3], v[6:7]
	v_pk_mul_f32 v[10:11], v[10:11], v[20:21]
	v_cvt_pk_bf16_f32 v5, v6, v7
	v_mad_i64_i32 v[6:7], s[40:41], v14, s68, v[122:123]
	v_cvt_pk_bf16_f32 v2, v10, v11
	v_cvt_pk_bf16_f32 v3, v12, v13
	v_cvt_pk_bf16_f32 v4, v8, v9
	v_lshl_add_u64 v[6:7], v[6:7], 0, v[110:111]
	global_store_dwordx4 v[6:7], v[2:5], off
	s_cbranch_vccnz .LBB0_301
	s_andn2_b64 vcc, exec, s[12:13]
	s_cbranch_vccnz .LBB0_300
	s_barrier
	s_branch .LBB0_300
